# stack + GEMM5 epilogue: all 16 residual loads issued together before any store, vmcnt ladder removed
# baseline (speedup 1.0000x reference)
; __device__ __forceinline__ float bflo(unsigned u) { return __uint_as_float(u << 16); }
; __device__ __forceinline__ float bfhi(unsigned u) { return __uint_as_float(u & 0xffff0000u); }
; #define LAS __attribute__((address_space(3)))
; __device__ __forceinline__ void attn_item(LAS unsigned char* lds, const bf16* P, bf16* Y, const float* qg, const float* kg, const float* sinks, int item, int tid) {
;     const int hkv = item & 1, nb = (item >> 1) & 15, b = item >> 5;
;     const int R0 = b * SEQ + nb * 128;
;     LAS bf16* Ks = (LAS bf16*)lds; LAS bf16* Vt = (LAS bf16*)(lds + 36864);
;     v4u qraw[4][2];
;     { const int w_ = tid >> 6, ln = tid & 63; const bf16* qp = P + (size_t)(R0 + (w_ & 1) * 64 + (ln & 15)) * PP + (hkv * 4 + (w_ >> 1)) * 64 + 8 * (ln >> 4);
; #pragma unroll
;       for (int it = 0; it < 4; ++it) { qraw[it][0] = *(const v4u*)(qp + (size_t)(16 * it) * PP); qraw[it][1] = *(const v4u*)(qp + (size_t)(16 * it) * PP + 32); } }
; #pragma unroll
;     for (int i = 0; i < 4; ++i) {
;         const int task = tid + 512 * i, key = task >> 3, c = task & 7; const bool ok = (nb > 0) || (key >= 128);
;         v4u kr = {0u, 0u, 0u, 0u}, vr = {0u, 0u, 0u, 0u};
;         if (ok) { const bf16* rp = P + (size_t)(R0 - 128 + key) * PP + hkv * 64 + 8 * c; kr = *(const v4u*)(rp + C_K); vr = *(const v4u*)(rp + C_V); }
;         float kf[8];
; #pragma unroll
;         for (int e = 0; e < 4; ++e) { kf[2 * e] = bflo(kr[e]); kf[2 * e + 1] = bfhi(kr[e]); }
;         float ss = 0.f;
; #pragma unroll
;         for (int e = 0; e < 8; ++e) ss += kf[e] * kf[e];
;         ss += __shfl_xor(ss, 1); ss += __shfl_xor(ss, 2); ss += __shfl_xor(ss, 4);
;         const float rs = rsqrtf(ss * (1.f / 64.f) + EPS);
.LBB0_132:
	s_andn2_b64 vcc, exec, s[18:19]
	s_cbranch_vccnz .LBB0_129
	s_bfe_u32 s3, s25, 0x40001
	s_lshl_b32 s22, s25, 6
	s_and_b32 s18, s22, 0xfffff800
	s_lshl_b32 s19, s3, 7
	s_and_b32 s2, s25, 1
	s_or_b32 s23, s19, s18
	v_or_b32_e32 v3, s23, v191
	v_mov_b64_e32 v[0:1], s[16:17]
	v_lshl_add_u32 v46, s2, 2, v192
	v_mad_i64_i32 v[4:5], s[18:19], v3, s36, v[0:1]
	v_lshlrev_b32_e32 v0, 6, v46
	v_ashrrev_i32_e32 v1, 31, v0
	v_lshl_add_u64 v[4:5], v[0:1], 1, v[4:5]
	v_mov_b32_e32 v123, v2
	v_lshl_add_u64 v[20:21], v[4:5], 0, v[122:123]
	global_load_dwordx4 v[160:163], v[104:105], off offset:16
	global_load_dwordx4 v[164:167], v[104:105], off
	v_ashrrev_i32_e32 v47, 31, v46
	v_lshl_add_u64 v[36:37], v[46:47], 2, s[42:43]
	global_load_dword v184, v[36:37], off
	global_load_dwordx4 v[168:171], v[108:109], off
	global_load_dwordx4 v[172:175], v[108:109], off offset:16
	global_load_dwordx4 v[176:179], v[108:109], off offset:128
	global_load_dwordx4 v[180:183], v[108:109], off offset:144
	s_mov_b32 s18, 0x17000
	v_add_co_u32_e32 v8, vcc, s18, v20
	s_mov_b32 s18, 0x2e000
	s_nop 0
	v_addc_co_u32_e32 v9, vcc, 0, v21, vcc
	v_add_co_u32_e32 v16, vcc, s18, v20
	s_mov_b32 s18, 0x45000
	s_nop 0
	v_addc_co_u32_e32 v17, vcc, 0, v21, vcc
	v_add_co_u32_e32 v24, vcc, s18, v20
	global_load_dwordx4 v[32:35], v[20:21], off
	global_load_dwordx4 v[28:31], v[20:21], off offset:64
	v_addc_co_u32_e32 v25, vcc, 0, v21, vcc
	global_load_dwordx4 v[4:7], v[8:9], off
	s_nop 0
	global_load_dwordx4 v[8:11], v[8:9], off offset:64
	s_nop 0
	global_load_dwordx4 v[12:15], v[16:17], off
	s_nop 0
	global_load_dwordx4 v[16:19], v[16:17], off offset:64
	s_nop 0
	global_load_dwordx4 v[20:23], v[24:25], off
	s_nop 0
	global_load_dwordx4 v[24:27], v[24:25], off offset:64
	v_readlane_b32 s18, v254, 31
	s_cmp_lg_u32 s3, 0
	v_readlane_b32 s19, v254, 32
	s_cselect_b64 s[44:45], -1, 0
	s_mov_b32 s29, s19
	s_lshl_b32 s28, s2, 7
	v_writelane_b32 v254, s18, 31
	s_addk_i32 s23, 0xff80
	v_lshl_add_u64 v[48:49], v[106:107], 0, s[28:29]
	v_writelane_b32 v254, s19, 32
	s_or_b64 s[28:29], s[64:65], s[44:45]
	v_mov_b32_e32 v64, 0
	v_mov_b32_e32 v65, 0
	v_mov_b32_e32 v66, 0
	v_mov_b32_e32 v67, 0
	v_mov_b32_e32 v68, 0
	v_mov_b32_e32 v69, 0
	v_mov_b32_e32 v70, 0
	v_mov_b32_e32 v71, 0
	v_mov_b32_e32 v76, 0
	v_mov_b32_e32 v77, 0
	v_mov_b32_e32 v78, 0
	v_mov_b32_e32 v79, 0
	v_mov_b32_e32 v80, 0
	v_mov_b32_e32 v81, 0
	v_mov_b32_e32 v82, 0
	v_mov_b32_e32 v83, 0
	v_mov_b32_e32 v84, 0
	v_mov_b32_e32 v85, 0
	v_mov_b32_e32 v86, 0
	v_mov_b32_e32 v87, 0
	v_mov_b32_e32 v88, 0
	v_mov_b32_e32 v89, 0
	v_mov_b32_e32 v90, 0
	v_mov_b32_e32 v91, 0
	v_mov_b32_e32 v92, 0
	v_mov_b32_e32 v93, 0
	v_mov_b32_e32 v94, 0
	v_mov_b32_e32 v95, 0
	v_mov_b32_e32 v96, 0
	v_mov_b32_e32 v97, 0
	v_mov_b32_e32 v98, 0
	v_mov_b32_e32 v99, 0
	s_or_b64 s[28:29], s[44:45], s[64:65]
	v_add_u32_e32 v37, s23, v193
	v_mad_i64_i32 v[38:39], s[18:19], v37, s36, v[48:49]
	s_and_saveexec_b64 s[34:35], s[28:29]
	global_load_dwordx4 v[64:67], v[38:39], off offset:1024
	global_load_dwordx4 v[68:71], v[38:39], off offset:1280
	s_or_b64 exec, exec, s[34:35]
	s_or_b64 s[28:29], s[44:45], s[84:85]
	v_add_u32_e32 v37, s23, v195
	v_mad_i64_i32 v[40:41], s[18:19], v37, s36, v[48:49]
	s_and_saveexec_b64 s[34:35], s[28:29]
	global_load_dwordx4 v[76:79], v[40:41], off offset:1024
	global_load_dwordx4 v[80:83], v[40:41], off offset:1280
	s_or_b64 exec, exec, s[34:35]
	s_or_b64 s[28:29], s[44:45], s[90:91]
	v_add_u32_e32 v37, s23, v203
	v_mad_i64_i32 v[42:43], s[18:19], v37, s36, v[48:49]
	s_and_saveexec_b64 s[34:35], s[28:29]
	global_load_dwordx4 v[84:87], v[42:43], off offset:1024
	global_load_dwordx4 v[88:91], v[42:43], off offset:1280
	s_or_b64 exec, exec, s[34:35]
	s_or_b64 s[28:29], s[44:45], s[92:93]
	v_add_u32_e32 v37, s23, v205
	v_mad_i64_i32 v[44:45], s[18:19], v37, s36, v[48:49]
	s_and_saveexec_b64 s[34:35], s[28:29]
	global_load_dwordx4 v[92:95], v[44:45], off offset:1024
	global_load_dwordx4 v[96:99], v[44:45], off offset:1280
	s_or_b64 exec, exec, s[34:35]
	v_and_b32_e32 v3, 64, v235
	v_add_u32_e32 v3, 64, v3
	v_xor_b32_e32 v37, 1, v235
	v_cmp_lt_i32_e32 vcc, v37, v3
	s_nop 1
	v_cndmask_b32_e32 v37, v235, v37, vcc
	v_lshlrev_b32_e32 v47, 2, v37
	v_xor_b32_e32 v37, 2, v235
	v_cmp_lt_i32_e32 vcc, v37, v3
	s_nop 1
	v_cndmask_b32_e32 v37, v235, v37, vcc
	v_lshlrev_b32_e32 v50, 2, v37
	v_xor_b32_e32 v37, 4, v235
	v_cmp_lt_i32_e32 vcc, v37, v3
	s_nop 1
	v_cndmask_b32_e32 v37, v235, v37, vcc
	v_lshlrev_b32_e32 v51, 2, v37
	s_waitcnt vmcnt(6)
	v_lshlrev_b32_e32 v56, 16, v64
	v_and_b32_e32 v57, 0xffff0000, v64
	v_lshlrev_b32_e32 v59, 16, v65
	v_and_b32_e32 v58, 0xffff0000, v65
	v_lshlrev_b32_e32 v61, 16, v66
	v_and_b32_e32 v60, 0xffff0000, v66
	v_lshlrev_b32_e32 v63, 16, v67
	v_and_b32_e32 v62, 0xffff0000, v67
	v_mul_f32_e32 v52, v56, v56
	v_mul_f32_e32 v37, v57, v57
	v_add_f32_e32 v52, v52, v37
	v_mul_f32_e32 v37, v59, v59
	v_add_f32_e32 v52, v37, v52
	v_mul_f32_e32 v37, v58, v58
	v_add_f32_e32 v52, v37, v52
	v_mul_f32_e32 v37, v61, v61
	v_add_f32_e32 v52, v37, v52
	v_mul_f32_e32 v37, v60, v60
	v_add_f32_e32 v52, v37, v52
	v_mul_f32_e32 v37, v63, v63
	v_add_f32_e32 v52, v37, v52
	v_mul_f32_e32 v37, v62, v62
	v_add_f32_e32 v52, v37, v52
	s_waitcnt vmcnt(4)
	v_lshlrev_b32_e32 v56, 16, v76
	v_and_b32_e32 v57, 0xffff0000, v76
	v_lshlrev_b32_e32 v59, 16, v77
	v_and_b32_e32 v58, 0xffff0000, v77
	v_lshlrev_b32_e32 v61, 16, v78
	v_and_b32_e32 v60, 0xffff0000, v78
	v_lshlrev_b32_e32 v63, 16, v79
	v_and_b32_e32 v62, 0xffff0000, v79
	v_mul_f32_e32 v53, v56, v56
	v_mul_f32_e32 v37, v57, v57
	v_add_f32_e32 v53, v53, v37
	v_mul_f32_e32 v37, v59, v59
	v_add_f32_e32 v53, v37, v53
	v_mul_f32_e32 v37, v58, v58
	v_add_f32_e32 v53, v37, v53
	v_mul_f32_e32 v37, v61, v61
	v_add_f32_e32 v53, v37, v53
	v_mul_f32_e32 v37, v60, v60
	v_add_f32_e32 v53, v37, v53
	v_mul_f32_e32 v37, v63, v63
	v_add_f32_e32 v53, v37, v53
	v_mul_f32_e32 v37, v62, v62
	v_add_f32_e32 v53, v37, v53
	s_waitcnt vmcnt(2)
; __device__ __forceinline__ unsigned cvt_pk_bf16(float lo, float hi) { unsigned r; asm volatile("v_cvt_pk_bf16_f32 %0, %1, %2" : "=v"(r) : "v"(lo), "v"(hi)); return r; }
; __device__ __forceinline__ float bflo(unsigned u) { return __uint_as_float(u << 16); }
; __device__ __forceinline__ float bfhi(unsigned u) { return __uint_as_float(u & 0xffff0000u); }
; #define LAS __attribute__((address_space(3)))
; __device__ __forceinline__ void attn_item(LAS unsigned char* lds, const bf16* P, bf16* Y, const float* qg, const float* kg, const float* sinks, int item, int tid) {
;     ...
;         for (int e = 0; e < 4; ++e) { kf[2 * e] = bflo(kr[e]); kf[2 * e + 1] = bfhi(kr[e]); }
;         float ss = 0.f;
; #pragma unroll
;         for (int e = 0; e < 8; ++e) ss += kf[e] * kf[e];
;         ss += __shfl_xor(ss, 1); ss += __shfl_xor(ss, 2); ss += __shfl_xor(ss, 4);
;         const float rs = rsqrtf(ss * (1.f / 64.f) + EPS);
;         const f32x4 g0 = *(const f32x4*)(kg + 8 * c), g1 = *(const f32x4*)(kg + 8 * c + 4);
;         v4u kw; kw.x = cvt_pk_bf16(kf[0] * rs * g0.x, kf[1] * rs * g0.y); kw.y = cvt_pk_bf16(kf[2] * rs * g0.z, kf[3] * rs * g0.w);
;         kw.z = cvt_pk_bf16(kf[4] * rs * g1.x, kf[5] * rs * g1.y); kw.w = cvt_pk_bf16(kf[6] * rs * g1.z, kf[7] * rs * g1.w);
;         *(LAS v4u*)(Ks + key * 72 + 8 * c) = kw;
; #pragma unroll
;         for (int e = 0; e < 4; ++e) { Vt[(8 * c + 2 * e) * 264 + key] = (bf16)(vr[e] & 0xffffu); Vt[(8 * c + 2 * e + 1) * 264 + key] = (bf16)(vr[e] >> 16); }
	v_lshlrev_b32_e32 v56, 16, v84
	v_and_b32_e32 v57, 0xffff0000, v84
	v_lshlrev_b32_e32 v59, 16, v85
	v_and_b32_e32 v58, 0xffff0000, v85
	v_lshlrev_b32_e32 v61, 16, v86
	v_and_b32_e32 v60, 0xffff0000, v86
	v_lshlrev_b32_e32 v63, 16, v87
	v_and_b32_e32 v62, 0xffff0000, v87
	v_mul_f32_e32 v54, v56, v56
	v_mul_f32_e32 v37, v57, v57
	v_add_f32_e32 v54, v54, v37
	v_mul_f32_e32 v37, v59, v59
	v_add_f32_e32 v54, v37, v54
	v_mul_f32_e32 v37, v58, v58
	v_add_f32_e32 v54, v37, v54
	v_mul_f32_e32 v37, v61, v61
	v_add_f32_e32 v54, v37, v54
	v_mul_f32_e32 v37, v60, v60
	v_add_f32_e32 v54, v37, v54
	v_mul_f32_e32 v37, v63, v63
	v_add_f32_e32 v54, v37, v54
	v_mul_f32_e32 v37, v62, v62
	v_add_f32_e32 v54, v37, v54
	s_waitcnt vmcnt(0)
	v_lshlrev_b32_e32 v56, 16, v92
	v_and_b32_e32 v57, 0xffff0000, v92
	v_lshlrev_b32_e32 v59, 16, v93
	v_and_b32_e32 v58, 0xffff0000, v93
	v_lshlrev_b32_e32 v61, 16, v94
	v_and_b32_e32 v60, 0xffff0000, v94
	v_lshlrev_b32_e32 v63, 16, v95
	v_and_b32_e32 v62, 0xffff0000, v95
	v_mul_f32_e32 v55, v56, v56
	v_mul_f32_e32 v37, v57, v57
	v_add_f32_e32 v55, v55, v37
	v_mul_f32_e32 v37, v59, v59
	v_add_f32_e32 v55, v37, v55
	v_mul_f32_e32 v37, v58, v58
	v_add_f32_e32 v55, v37, v55
	v_mul_f32_e32 v37, v61, v61
	v_add_f32_e32 v55, v37, v55
	v_mul_f32_e32 v37, v60, v60
	v_add_f32_e32 v55, v37, v55
	v_mul_f32_e32 v37, v63, v63
	v_add_f32_e32 v55, v37, v55
	v_mul_f32_e32 v37, v62, v62
	v_add_f32_e32 v55, v37, v55
	ds_bpermute_b32 v40, v47, v52
	ds_bpermute_b32 v41, v47, v53
	ds_bpermute_b32 v42, v47, v54
	ds_bpermute_b32 v43, v47, v55
	s_waitcnt lgkmcnt(0)
	v_add_f32_e32 v52, v52, v40
	v_add_f32_e32 v53, v53, v41
	v_add_f32_e32 v54, v54, v42
	v_add_f32_e32 v55, v55, v43
	ds_bpermute_b32 v40, v50, v52
	ds_bpermute_b32 v41, v50, v53
	ds_bpermute_b32 v42, v50, v54
	ds_bpermute_b32 v43, v50, v55
	s_waitcnt lgkmcnt(0)
	v_add_f32_e32 v52, v52, v40
	v_add_f32_e32 v53, v53, v41
	v_add_f32_e32 v54, v54, v42
	v_add_f32_e32 v55, v55, v43
	ds_bpermute_b32 v40, v51, v52
	ds_bpermute_b32 v41, v51, v53
	ds_bpermute_b32 v42, v51, v54
	ds_bpermute_b32 v43, v51, v55
	s_waitcnt lgkmcnt(0)
	v_add_f32_e32 v52, v52, v40
	v_add_f32_e32 v53, v53, v41
	v_add_f32_e32 v54, v54, v42
	v_add_f32_e32 v55, v55, v43
	v_fmamk_f32 v52, v52, 0x3c800000, v196
	v_cmp_gt_f32_e32 vcc, s13, v52
	v_mul_f32_e32 v37, 0x4b800000, v52
	s_nop 0
	v_cndmask_b32_e32 v52, v52, v37, vcc
	v_rsq_f32_e32 v52, v52
	s_nop 0
	v_mul_f32_e32 v37, 0x45800000, v52
	v_cndmask_b32_e32 v52, v52, v37, vcc
	v_fmamk_f32 v53, v53, 0x3c800000, v196
	v_cmp_gt_f32_e32 vcc, s13, v53
	v_mul_f32_e32 v37, 0x4b800000, v53
	s_nop 0
	v_cndmask_b32_e32 v53, v53, v37, vcc
	v_rsq_f32_e32 v53, v53
	s_nop 0
	v_mul_f32_e32 v37, 0x45800000, v53
	v_cndmask_b32_e32 v53, v53, v37, vcc
	v_fmamk_f32 v54, v54, 0x3c800000, v196
	v_cmp_gt_f32_e32 vcc, s13, v54
	v_mul_f32_e32 v37, 0x4b800000, v54
	s_nop 0
	v_cndmask_b32_e32 v54, v54, v37, vcc
	v_rsq_f32_e32 v54, v54
	s_nop 0
	v_mul_f32_e32 v37, 0x45800000, v54
	v_cndmask_b32_e32 v54, v54, v37, vcc
	v_fmamk_f32 v55, v55, 0x3c800000, v196
	v_cmp_gt_f32_e32 vcc, s13, v55
	v_mul_f32_e32 v37, 0x4b800000, v55
	s_nop 0
	v_cndmask_b32_e32 v55, v55, v37, vcc
	v_rsq_f32_e32 v55, v55
	s_nop 0
	v_mul_f32_e32 v37, 0x45800000, v55
	v_cndmask_b32_e32 v55, v55, v37, vcc
	v_lshlrev_b32_e32 v56, 16, v64
	v_and_b32_e32 v57, 0xffff0000, v64
	v_lshlrev_b32_e32 v59, 16, v65
	v_and_b32_e32 v58, 0xffff0000, v65
	v_lshlrev_b32_e32 v61, 16, v66
	v_and_b32_e32 v60, 0xffff0000, v66
	v_lshlrev_b32_e32 v63, 16, v67
	v_and_b32_e32 v62, 0xffff0000, v67
	v_mul_f32_e32 v56, v52, v56
	v_mul_f32_e32 v56, v164, v56
	v_mul_f32_e32 v57, v52, v57
	v_mul_f32_e32 v57, v165, v57
	v_mul_f32_e32 v59, v52, v59
	v_mul_f32_e32 v59, v166, v59
	v_mul_f32_e32 v58, v52, v58
	v_mul_f32_e32 v58, v167, v58
	v_mul_f32_e32 v61, v52, v61
	v_mul_f32_e32 v61, v160, v61
	v_mul_f32_e32 v60, v52, v60
	v_mul_f32_e32 v60, v161, v60
	v_mul_f32_e32 v63, v52, v63
	v_mul_f32_e32 v63, v162, v63
	v_mul_f32_e32 v62, v52, v62
	v_mul_f32_e32 v62, v163, v62
	v_cvt_pk_bf16_f32 v40, v56, v57
	v_cvt_pk_bf16_f32 v41, v59, v58
	v_cvt_pk_bf16_f32 v42, v61, v60
	v_cvt_pk_bf16_f32 v43, v63, v62
	ds_write_b128 v219, v[40:43]
	ds_write_b16 v194, v68 offset:36864
	ds_write_b16_d16_hi v194, v68 offset:37392
	ds_write_b16 v194, v69 offset:37920
	ds_write_b16_d16_hi v194, v69 offset:38448
	ds_write_b16 v194, v70 offset:38976
	ds_write_b16_d16_hi v194, v70 offset:39504
	ds_write_b16 v194, v71 offset:40032
	ds_write_b16_d16_hi v194, v71 offset:40560
	v_lshlrev_b32_e32 v56, 16, v76
	v_and_b32_e32 v57, 0xffff0000, v76
	v_lshlrev_b32_e32 v59, 16, v77
	v_and_b32_e32 v58, 0xffff0000, v77
	v_lshlrev_b32_e32 v61, 16, v78
	v_and_b32_e32 v60, 0xffff0000, v78
	v_lshlrev_b32_e32 v63, 16, v79
	v_and_b32_e32 v62, 0xffff0000, v79
	v_mul_f32_e32 v56, v53, v56
	v_mul_f32_e32 v56, v164, v56
	v_mul_f32_e32 v57, v53, v57
	v_mul_f32_e32 v57, v165, v57
	v_mul_f32_e32 v59, v53, v59
	v_mul_f32_e32 v59, v166, v59
	v_mul_f32_e32 v58, v53, v58
	v_mul_f32_e32 v58, v167, v58
	v_mul_f32_e32 v61, v53, v61
	v_mul_f32_e32 v61, v160, v61
	v_mul_f32_e32 v60, v53, v60
	v_mul_f32_e32 v60, v161, v60
	v_mul_f32_e32 v63, v53, v63
	v_mul_f32_e32 v63, v162, v63
	v_mul_f32_e32 v62, v53, v62
	v_mul_f32_e32 v62, v163, v62
	v_cvt_pk_bf16_f32 v40, v56, v57
	v_cvt_pk_bf16_f32 v41, v59, v58
	v_cvt_pk_bf16_f32 v42, v61, v60
	v_cvt_pk_bf16_f32 v43, v63, v62
; #define LAS __attribute__((address_space(3)))
; __device__ __forceinline__ void attn_item(LAS unsigned char* lds, const bf16* P, bf16* Y, const float* qg, const float* kg, const float* sinks, int item, int tid) {
;     ...
;         *(LAS v4u*)(Ks + key * 72 + 8 * c) = kw;
; #pragma unroll
;         for (int e = 0; e < 4; ++e) { Vt[(8 * c + 2 * e) * 264 + key] = (bf16)(vr[e] & 0xffffu); Vt[(8 * c + 2 * e + 1) * 264 + key] = (bf16)(vr[e] >> 16); }
;     }
;     __syncthreads();
;     const int w = tid >> 6, lane = tid & 63, fr = lane & 15, fq = lane >> 4, g = w >> 1, h = hkv * 4 + g, half = w & 1;
;     const float slope2 = exp2f(-(float)(h + 1)) * LOG2E, sink2 = sinks[h] * LOG2E;
;     f32x4 qgv[4];
; #pragma unroll
;     for (int ks = 0; ks < 2; ++ks) { qgv[2 * ks] = *(const f32x4*)(qg + 32 * ks + 8 * fq); qgv[2 * ks + 1] = *(const f32x4*)(qg + 32 * ks + 8 * fq + 4); }
	ds_write_b128 v220, v[40:43]
	ds_write_b16 v202, v80 offset:36864
	ds_write_b16_d16_hi v202, v80 offset:37392
	ds_write_b16 v202, v81 offset:37920
	ds_write_b16_d16_hi v202, v81 offset:38448
	ds_write_b16 v202, v82 offset:38976
	ds_write_b16_d16_hi v202, v82 offset:39504
	ds_write_b16 v202, v83 offset:40032
	ds_write_b16_d16_hi v202, v83 offset:40560
	v_lshlrev_b32_e32 v56, 16, v84
	v_and_b32_e32 v57, 0xffff0000, v84
	v_lshlrev_b32_e32 v59, 16, v85
	v_and_b32_e32 v58, 0xffff0000, v85
	v_lshlrev_b32_e32 v61, 16, v86
	v_and_b32_e32 v60, 0xffff0000, v86
	v_lshlrev_b32_e32 v63, 16, v87
	v_and_b32_e32 v62, 0xffff0000, v87
	v_mul_f32_e32 v56, v54, v56
	v_mul_f32_e32 v56, v164, v56
	v_mul_f32_e32 v57, v54, v57
	v_mul_f32_e32 v57, v165, v57
	v_mul_f32_e32 v59, v54, v59
	v_mul_f32_e32 v59, v166, v59
	v_mul_f32_e32 v58, v54, v58
	v_mul_f32_e32 v58, v167, v58
	v_mul_f32_e32 v61, v54, v61
	v_mul_f32_e32 v61, v160, v61
	v_mul_f32_e32 v60, v54, v60
	v_mul_f32_e32 v60, v161, v60
	v_mul_f32_e32 v63, v54, v63
	v_mul_f32_e32 v63, v162, v63
	v_mul_f32_e32 v62, v54, v62
	v_mul_f32_e32 v62, v163, v62
	v_cvt_pk_bf16_f32 v40, v56, v57
	v_cvt_pk_bf16_f32 v41, v59, v58
	v_cvt_pk_bf16_f32 v42, v61, v60
	v_cvt_pk_bf16_f32 v43, v63, v62
	ds_write_b128 v221, v[40:43]
	ds_write_b16 v204, v88 offset:36864
	ds_write_b16_d16_hi v204, v88 offset:37392
	ds_write_b16 v204, v89 offset:37920
	ds_write_b16_d16_hi v204, v89 offset:38448
	ds_write_b16 v204, v90 offset:38976
	ds_write_b16_d16_hi v204, v90 offset:39504
	ds_write_b16 v204, v91 offset:40032
	ds_write_b16_d16_hi v204, v91 offset:40560
	v_lshlrev_b32_e32 v56, 16, v92
	v_and_b32_e32 v57, 0xffff0000, v92
	v_lshlrev_b32_e32 v59, 16, v93
	v_and_b32_e32 v58, 0xffff0000, v93
	v_lshlrev_b32_e32 v61, 16, v94
	v_and_b32_e32 v60, 0xffff0000, v94
	v_lshlrev_b32_e32 v63, 16, v95
	v_and_b32_e32 v62, 0xffff0000, v95
	v_mul_f32_e32 v56, v55, v56
	v_mul_f32_e32 v56, v164, v56
	v_mul_f32_e32 v57, v55, v57
	v_mul_f32_e32 v57, v165, v57
	v_mul_f32_e32 v59, v55, v59
	v_mul_f32_e32 v59, v166, v59
	v_mul_f32_e32 v58, v55, v58
	v_mul_f32_e32 v58, v167, v58
	v_mul_f32_e32 v61, v55, v61
	v_mul_f32_e32 v61, v160, v61
	v_mul_f32_e32 v60, v55, v60
	v_mul_f32_e32 v60, v161, v60
	v_mul_f32_e32 v63, v55, v63
	v_mul_f32_e32 v63, v162, v63
	v_mul_f32_e32 v62, v55, v62
	v_mul_f32_e32 v62, v163, v62
	v_cvt_pk_bf16_f32 v40, v56, v57
	v_cvt_pk_bf16_f32 v41, v59, v58
	v_cvt_pk_bf16_f32 v42, v61, v60
	v_cvt_pk_bf16_f32 v43, v63, v62
	ds_write_b128 v222, v[40:43]
	ds_write_b16 v206, v96 offset:36864
	ds_write_b16_d16_hi v206, v96 offset:37392
	ds_write_b16 v206, v97 offset:37920
	ds_write_b16_d16_hi v206, v97 offset:38448
	ds_write_b16 v206, v98 offset:38976
	ds_write_b16_d16_hi v206, v98 offset:39504
	ds_write_b16 v206, v99 offset:40032
	ds_write_b16_d16_hi v206, v99 offset:40560
	s_and_b32 s18, s24, 0xfffff800
	v_or_b32_e32 v44, s18, v191
	s_and_b32 s18, s22, 0x780
	v_or_b32_e32 v72, s18, v44
	s_mov_b32 s2, 0
	s_mov_b32 s18, 0x42fc0000
	s_cmp_eq_u32 s3, 0
	s_cselect_b64 s[62:63], -1, 0
	v_lshl_add_u64 v[74:75], v[0:1], 1, v[110:111]
	v_mov_b32_e32 v0, v218
	v_mov_b32_e32 v133, v215
	v_add_u32_e32 v36, 1, v46
	v_cvt_f32_i32_e32 v36, v36
	v_mov_b32_e32 v37, 0x42800000
	v_ashrrev_i32_e32 v47, 31, v46
	v_cmp_lt_f32_e32 vcc, s18, v36
	s_waitcnt lgkmcnt(0)
	s_barrier
	v_cndmask_b32_e32 v37, 0, v37, vcc
	v_sub_f32_e32 v36, v37, v36
	v_exp_f32_e32 v36, v36
	v_not_b32_e32 v37, 63
	v_cndmask_b32_e32 v37, 0, v37, vcc
	v_ldexp_f32 v52, v36, v37
	v_mov_b32_e32 v53, v184
	v_mov_b32_e32 v36, v168
	v_mov_b32_e32 v37, v169
	v_mov_b32_e32 v38, v170
	v_mov_b32_e32 v39, v171
	v_mov_b32_e32 v40, v172
	v_mov_b32_e32 v41, v173
	v_mov_b32_e32 v42, v174
	v_mov_b32_e32 v43, v175
	v_mov_b32_e32 v44, v176
	v_mov_b32_e32 v45, v177
	v_mov_b32_e32 v46, v178
	v_mov_b32_e32 v47, v179
	v_mov_b32_e32 v48, v180
	v_mov_b32_e32 v49, v181
	v_mov_b32_e32 v50, v182
	v_mov_b32_e32 v51, v183
	s_add_i32 s18, s25, s12
	s_cmpk_gt_i32 s18, 0x2ff
	s_cbranch_scc1 .Lpf_done
	s_cmpk_gt_i32 s18, 0x1ff
	s_cbranch_scc1 .Lpf_sgu
	s_lshl_b32 s19, s18, 6
	s_and_b32 s28, s19, 0xfffff800
	s_bfe_u32 s29, s18, 0x40001
	s_lshl_b32 s29, s29, 7
	s_or_b32 s28, s28, s29
	s_and_b32 s29, s18, 1
	v_lshrrev_b32_e32 v164, 2, v242
	v_add_u32_e32 v164, s28, v164
	v_mul_lo_u32 v164, v164, s36
	v_and_b32_e32 v165, 3, v242
	v_lshlrev_b32_e32 v165, 7, v165
	s_lshl_b32 s19, s29, 9
	v_add3_u32 v164, v164, v165, s19
	v_mov_b32_e32 v165, 0
	v_lshl_add_u64 v[166:167], v[164:165], 0, s[16:17]
	global_load_dword v168, v[166:167], off
	v_lshrrev_b32_e32 v164, 1, v242
	v_add_u32_e32 v164, s28, v164
	v_subrev_u32_e32 v164, 0x80, v164
	v_max_i32_e32 v164, 0, v164
	v_mul_lo_u32 v164, v164, s36
	v_and_b32_e32 v165, 1, v242
	v_lshlrev_b32_e32 v165, 8, v165
	s_lshl_b32 s19, s29, 7
	s_addk_i32 s19, 0x400
	v_add3_u32 v164, v164, v165, s19
	v_mov_b32_e32 v165, 0
	v_lshl_add_u64 v[166:167], v[164:165], 0, s[16:17]
	global_load_dword v169, v[166:167], off
	s_branch .Lpf_done
.Lpf_sgu:
	s_lshl_b32 s28, s18, 7
	s_add_i32 s28, s28, 0xffff0000
	v_lshrrev_b32_e32 v164, 2, v242
	v_add_u32_e32 v164, s28, v164
	v_mul_lo_u32 v164, v164, s36
	v_and_b32_e32 v165, 3, v242
	v_lshlrev_b32_e32 v165, 8, v165
	v_add_u32_e32 v164, v164, v165
	v_mov_b32_e32 v165, 0
	v_lshl_add_u64 v[166:167], v[164:165], 0, s[16:17]
	global_load_dword v168, v[166:167], off offset:2560
	global_load_dword v169, v[166:167], off offset:2688

; __device__ __forceinline__ float bflo(unsigned u) { return __uint_as_float(u << 16); }
; __device__ __forceinline__ float bfhi(unsigned u) { return __uint_as_float(u & 0xffff0000u); }
;     __device__ __forceinline__ void operator()(const f32x4 (&acc)[2][2][4][2], const Unit& u, int wr, int wc, int fr, int fq) const {
;     ...
;                 u32x4 rb[4][2];
; #pragma unroll
;                 for (int m = 0; m < 4; ++m) { const size_t off = (size_t)(row0 + ai * HALF + m * 16) * ldc + col0;
; #pragma unroll
;                     for (int bj = 0; bj < 2; ++bj) rb[m][bj] = *(const u32x4*)(baseb + off + bj * HALF); }
; #pragma unroll
;                 for (int m = 0; m < 4; ++m)
; #pragma unroll
;                     for (int bj = 0; bj < 2; ++bj) { bs[m][bj][0] = (f32x4){bflo(rb[m][bj].x), bfhi(rb[m][bj].x), bflo(rb[m][bj].y), bfhi(rb[m][bj].y)}; bs[m][bj][1] = (f32x4){bflo(rb[m][bj].z), bfhi(rb[m][bj].z), bflo(rb[m][bj].w), bfhi(rb[m][bj].w)}; }
;             }
; #pragma unroll
;             for (int m = 0; m < 4; ++m) { const size_t off = (size_t)(row0 + ai * HALF + m * 16) * ldc + col0; float ss = 0.f;
; #pragma unroll
;                 for (int bj = 0; bj < 2; ++bj) { const f32x4 o0 = bs[m][bj][0] + acc[ai][bj][m][0], o1 = bs[m][bj][1] + acc[ai][bj][m][1];
;                     if (outf) { *(f32x4*)(outf + off + bj * HALF) = o0; *(f32x4*)(outf + off + bj * HALF + 4) = o1; }
.LBB0_175:
	v_lshl_add_u32 v174, s63, 8, v3
	v_lshl_or_b32 v170, s64, 8, v187
	v_ashrrev_i32_e32 v171, 31, v170
	v_ashrrev_i32_e32 v175, 31, v174
	v_lshl_add_u64 v[172:173], v[170:171], 1, s[14:15]
	v_lshlrev_b64 v[124:125], 11, v[174:175]
	v_or_b32_e32 v180, 16, v174
	v_lshl_add_u64 v[124:125], v[172:173], 0, v[124:125]
	v_ashrrev_i32_e32 v181, 31, v180
	global_load_dwordx4 v[190:193], v[124:125], off
	global_load_dwordx4 v[156:159], v[124:125], off offset:256
	v_lshlrev_b64 v[124:125], 11, v[180:181]
	v_or_b32_e32 v178, 32, v174
	v_lshl_add_u64 v[124:125], v[172:173], 0, v[124:125]
	v_ashrrev_i32_e32 v179, 31, v178
	global_load_dwordx4 v[152:155], v[124:125], off
	global_load_dwordx4 v[148:151], v[124:125], off offset:256
	v_lshlrev_b64 v[124:125], 11, v[178:179]
	v_or_b32_e32 v176, 48, v174
	v_lshl_add_u64 v[124:125], v[172:173], 0, v[124:125]
	v_ashrrev_i32_e32 v177, 31, v176
	global_load_dwordx4 v[144:147], v[124:125], off
	global_load_dwordx4 v[140:143], v[124:125], off offset:256
	v_lshlrev_b64 v[124:125], 11, v[176:177]
	v_lshl_add_u64 v[124:125], v[172:173], 0, v[124:125]
	global_load_dwordx4 v[136:139], v[124:125], off
	s_nop 0
	global_load_dwordx4 v[124:127], v[124:125], off offset:256
	v_add_u32_e32 v244, 0x80, v174
	v_ashrrev_i32_e32 v245, 31, v244
	v_lshlrev_b64 v[244:245], 11, v[244:245]
	v_lshl_add_u64 v[244:245], v[172:173], 0, v[244:245]
	global_load_dwordx4 v[202:205], v[244:245], off
	global_load_dwordx4 v[206:209], v[244:245], off offset:256
	v_add_u32_e32 v244, 0x90, v174
	v_ashrrev_i32_e32 v245, 31, v244
	v_lshlrev_b64 v[244:245], 11, v[244:245]
	v_lshl_add_u64 v[244:245], v[172:173], 0, v[244:245]
	global_load_dwordx4 v[210:213], v[244:245], off
	global_load_dwordx4 v[214:217], v[244:245], off offset:256
	v_add_u32_e32 v244, 0xa0, v174
	v_ashrrev_i32_e32 v245, 31, v244
	v_lshlrev_b64 v[244:245], 11, v[244:245]
	v_lshl_add_u64 v[244:245], v[172:173], 0, v[244:245]
	global_load_dwordx4 v[218:221], v[244:245], off
	global_load_dwordx4 v[222:225], v[244:245], off offset:256
	v_add_u32_e32 v244, 0xb0, v174
	v_ashrrev_i32_e32 v245, 31, v244
	v_lshlrev_b64 v[244:245], 11, v[244:245]
	v_lshl_add_u64 v[244:245], v[172:173], 0, v[244:245]
	global_load_dwordx4 v[226:229], v[244:245], off
	global_load_dwordx4 v[230:233], v[244:245], off offset:256
	v_cndmask_b32_e64 v182, 0, 1, s[52:53]
	v_cmp_ne_u32_e64 s[42:43], 1, v182
	v_lshlrev_b64 v[182:183], 10, v[174:175]
	v_lshl_add_u64 v[182:183], v[182:183], 0, v[170:171]
	s_mov_b64 s[18:19], -1
	s_andn2_b64 vcc, exec, s[52:53]
	s_waitcnt vmcnt(0)
	v_lshlrev_b32_e32 v184, 16, v190
	v_and_b32_e32 v185, 0xffff0000, v190
	v_lshlrev_b32_e32 v190, 16, v191
	v_and_b32_e32 v191, 0xffff0000, v191
	v_lshlrev_b32_e32 v194, 16, v192
	v_and_b32_e32 v195, 0xffff0000, v192
	v_lshlrev_b32_e32 v192, 16, v193
	v_and_b32_e32 v193, 0xffff0000, v193
	v_pk_add_f32 v[134:135], v[134:135], v[190:191]
	v_pk_add_f32 v[132:133], v[132:133], v[184:185]
	v_pk_add_f32 v[130:131], v[130:131], v[192:193]
	v_pk_add_f32 v[128:129], v[128:129], v[194:195]
	v_lshl_add_u64 v[184:185], v[182:183], 2, s[48:49]
	s_cbranch_vccnz .LBB0_177
	s_mov_b64 s[18:19], 0
	global_store_dwordx4 v[184:185], v[132:135], off
	global_store_dwordx4 v[184:185], v[128:131], off offset:16

; __device__ __forceinline__ float bflo(unsigned u) { return __uint_as_float(u << 16); }
; __device__ __forceinline__ float bfhi(unsigned u) { return __uint_as_float(u & 0xffff0000u); }
;     __device__ __forceinline__ void operator()(const f32x4 (&acc)[2][2][4][2], const Unit& u, int wr, int wc, int fr, int fq) const {
;     ...
;                 for (int m = 0; m < 4; ++m)
; #pragma unroll
;                     for (int bj = 0; bj < 2; ++bj) { bs[m][bj][0] = (f32x4){bflo(rb[m][bj].x), bfhi(rb[m][bj].x), bflo(rb[m][bj].y), bfhi(rb[m][bj].y)}; bs[m][bj][1] = (f32x4){bflo(rb[m][bj].z), bfhi(rb[m][bj].z), bflo(rb[m][bj].w), bfhi(rb[m][bj].w)}; }
;             }
; #pragma unroll
;             for (int m = 0; m < 4; ++m) { const size_t off = (size_t)(row0 + ai * HALF + m * 16) * ldc + col0; float ss = 0.f;
; #pragma unroll
;                 for (int bj = 0; bj < 2; ++bj) { const f32x4 o0 = bs[m][bj][0] + acc[ai][bj][m][0], o1 = bs[m][bj][1] + acc[ai][bj][m][1];
;                     if (outf) { *(f32x4*)(outf + off + bj * HALF) = o0; *(f32x4*)(outf + off + bj * HALF + 4) = o1; }
.LBB0_220:
	v_add_u32_e32 v102, 0x80, v174
	v_ashrrev_i32_e32 v103, 31, v102
	s_waitcnt lgkmcnt(0)
	v_lshlrev_b64 v[68:69], 11, v[102:103]
	v_add_u32_e32 v100, 0x90, v174
	v_lshl_add_u64 v[68:69], v[172:173], 0, v[68:69]
	v_ashrrev_i32_e32 v101, 31, v100
	v_lshlrev_b64 v[68:69], 11, v[100:101]
	v_add_u32_e32 v98, 0xa0, v174
	v_lshl_add_u64 v[68:69], v[172:173], 0, v[68:69]
	v_ashrrev_i32_e32 v99, 31, v98
	v_lshlrev_b64 v[68:69], 11, v[98:99]
	v_add_u32_e32 v96, 0xb0, v174
	v_lshl_add_u64 v[68:69], v[172:173], 0, v[68:69]
	v_ashrrev_i32_e32 v97, 31, v96
	v_lshlrev_b64 v[68:69], 11, v[96:97]
	v_lshl_add_u64 v[68:69], v[172:173], 0, v[68:69]
	s_nop 0
	v_lshlrev_b64 v[104:105], 10, v[102:103]
	v_lshl_add_u64 v[104:105], v[104:105], 0, v[170:171]
	s_mov_b64 s[18:19], -1
	s_and_b64 vcc, exec, s[42:43]
	v_lshlrev_b32_e32 v110, 16, v202
	v_and_b32_e32 v111, 0xffff0000, v202
	v_lshlrev_b32_e32 v106, 16, v203
	v_and_b32_e32 v107, 0xffff0000, v203
	v_lshlrev_b32_e32 v112, 16, v204
	v_and_b32_e32 v113, 0xffff0000, v204
	v_lshlrev_b32_e32 v108, 16, v205
	v_and_b32_e32 v109, 0xffff0000, v205
	v_pk_add_f32 v[66:67], v[66:67], v[106:107]
	v_pk_add_f32 v[64:65], v[64:65], v[110:111]
	v_pk_add_f32 v[62:63], v[62:63], v[108:109]
	v_pk_add_f32 v[60:61], v[60:61], v[112:113]
	v_lshl_add_u64 v[106:107], v[104:105], 2, s[48:49]
	s_cbranch_vccnz .LBB0_222
	s_mov_b64 s[18:19], 0
	global_store_dwordx4 v[106:107], v[64:67], off
	global_store_dwordx4 v[106:107], v[60:63], off offset:16

; __device__ __forceinline__ unsigned cvt_pk_bf16(float lo, float hi) { unsigned r; asm volatile("v_cvt_pk_bf16_f32 %0, %1, %2" : "=v"(r) : "v"(lo), "v"(hi)); return r; }
; __device__ __forceinline__ float bflo(unsigned u) { return __uint_as_float(u << 16); }
; __device__ __forceinline__ float bfhi(unsigned u) { return __uint_as_float(u & 0xffff0000u); }
;     __device__ __forceinline__ void operator()(const f32x4 (&acc)[2][2][4][2], const Unit& u, int wr, int wc, int fr, int fq) const {
;     ...
;                     for (int bj = 0; bj < 2; ++bj) { bs[m][bj][0] = (f32x4){bflo(rb[m][bj].x), bfhi(rb[m][bj].x), bflo(rb[m][bj].y), bfhi(rb[m][bj].y)}; bs[m][bj][1] = (f32x4){bflo(rb[m][bj].z), bfhi(rb[m][bj].z), bflo(rb[m][bj].w), bfhi(rb[m][bj].w)}; }
;             }
; #pragma unroll
;             for (int m = 0; m < 4; ++m) { const size_t off = (size_t)(row0 + ai * HALF + m * 16) * ldc + col0; float ss = 0.f;
; #pragma unroll
;                 for (int bj = 0; bj < 2; ++bj) { const f32x4 o0 = bs[m][bj][0] + acc[ai][bj][m][0], o1 = bs[m][bj][1] + acc[ai][bj][m][1];
;                     if (outf) { *(f32x4*)(outf + off + bj * HALF) = o0; *(f32x4*)(outf + off + bj * HALF + 4) = o1; }
;                     else { ss += ((o0[0] * o0[0] + o0[1] * o0[1]) + (o0[2] * o0[2] + o0[3] * o0[3])) + ((o1[0] * o1[0] + o1[1] * o1[1]) + (o1[2] * o1[2] + o1[3] * o1[3]));
;                         u32x4 w; w.x = cvt_pk_bf16(o0[0], o0[1]); w.y = cvt_pk_bf16(o0[2], o0[3]); w.z = cvt_pk_bf16(o1[0], o1[1]); w.w = cvt_pk_bf16(o1[2], o1[3]); *(u32x4*)(outb + off + bj * HALF) = w; } }
.LBB0_224:
	v_lshlrev_b32_e32 v60, 16, v206
	v_and_b32_e32 v61, 0xffff0000, v206
	v_lshlrev_b32_e32 v62, 16, v207
	v_and_b32_e32 v63, 0xffff0000, v207
	v_lshlrev_b32_e32 v64, 16, v208
	v_and_b32_e32 v65, 0xffff0000, v208
	v_lshlrev_b32_e32 v66, 16, v209
	v_and_b32_e32 v67, 0xffff0000, v209
	v_pk_add_f32 v[58:59], v[58:59], v[62:63]
	v_pk_add_f32 v[56:57], v[56:57], v[60:61]
	v_pk_add_f32 v[54:55], v[54:55], v[66:67]
	v_pk_add_f32 v[52:53], v[52:53], v[64:65]
	s_and_b64 vcc, exec, s[42:43]
	s_mov_b64 s[18:19], -1
	s_cbranch_vccz .LBB0_227
	s_andn2_b64 vcc, exec, s[18:19]
	s_cbranch_vccz .LBB0_228

; __device__ __forceinline__ unsigned cvt_pk_bf16(float lo, float hi) { unsigned r; asm volatile("v_cvt_pk_bf16_f32 %0, %1, %2" : "=v"(r) : "v"(lo), "v"(hi)); return r; }
; __device__ __forceinline__ float bflo(unsigned u) { return __uint_as_float(u << 16); }
; __device__ __forceinline__ float bfhi(unsigned u) { return __uint_as_float(u & 0xffff0000u); }
;     __device__ __forceinline__ void operator()(const f32x4 (&acc)[2][2][4][2], const Unit& u, int wr, int wc, int fr, int fq) const {
;     ...
;                     for (int bj = 0; bj < 2; ++bj) { bs[m][bj][0] = (f32x4){bflo(rb[m][bj].x), bfhi(rb[m][bj].x), bflo(rb[m][bj].y), bfhi(rb[m][bj].y)}; bs[m][bj][1] = (f32x4){bflo(rb[m][bj].z), bfhi(rb[m][bj].z), bflo(rb[m][bj].w), bfhi(rb[m][bj].w)}; }
;             }
; #pragma unroll
;             for (int m = 0; m < 4; ++m) { const size_t off = (size_t)(row0 + ai * HALF + m * 16) * ldc + col0; float ss = 0.f;
; #pragma unroll
;                 for (int bj = 0; bj < 2; ++bj) { const f32x4 o0 = bs[m][bj][0] + acc[ai][bj][m][0], o1 = bs[m][bj][1] + acc[ai][bj][m][1];
;                     if (outf) { *(f32x4*)(outf + off + bj * HALF) = o0; *(f32x4*)(outf + off + bj * HALF + 4) = o1; }
;                     else { ss += ((o0[0] * o0[0] + o0[1] * o0[1]) + (o0[2] * o0[2] + o0[3] * o0[3])) + ((o1[0] * o1[0] + o1[1] * o1[1]) + (o1[2] * o1[2] + o1[3] * o1[3]));
;                         u32x4 w; w.x = cvt_pk_bf16(o0[0], o0[1]); w.y = cvt_pk_bf16(o0[2], o0[3]); w.z = cvt_pk_bf16(o1[0], o1[1]); w.w = cvt_pk_bf16(o1[2], o1[3]); *(u32x4*)(outb + off + bj * HALF) = w; } }
.LBB0_232:
	v_lshlrev_b32_e32 v54, 16, v210
	v_and_b32_e32 v55, 0xffff0000, v210
	v_lshlrev_b32_e32 v56, 16, v211
	v_and_b32_e32 v57, 0xffff0000, v211
	v_lshlrev_b32_e32 v58, 16, v212
	v_and_b32_e32 v59, 0xffff0000, v212
	v_lshlrev_b32_e32 v60, 16, v213
	v_and_b32_e32 v61, 0xffff0000, v213
	s_waitcnt lgkmcnt(0)
	v_lshlrev_b64 v[52:53], 10, v[100:101]
	v_lshl_add_u64 v[52:53], v[52:53], 0, v[170:171]
	v_pk_add_f32 v[50:51], v[50:51], v[56:57]
	v_pk_add_f32 v[48:49], v[48:49], v[54:55]
	v_pk_add_f32 v[46:47], v[46:47], v[60:61]
	s_cmp_eq_u64 s[18:19], 0
	v_pk_add_f32 v[44:45], v[44:45], v[58:59]
	s_cbranch_scc1 .LBB0_271
	v_lshlrev_b64 v[54:55], 2, v[52:53]
	v_lshl_add_u64 v[56:57], s[18:19], 0, v[54:55]
	v_lshl_add_u64 v[54:55], s[6:7], 0, v[54:55]
	global_store_dwordx4 v[56:57], v[48:51], off
	global_store_dwordx4 v[54:55], v[44:47], off offset:16
	v_mov_b32_e32 v56, 0
	v_lshl_add_u64 v[54:55], v[52:53], 1, s[6:7]
	s_cbranch_execnz .LBB0_235

; __device__ __forceinline__ unsigned cvt_pk_bf16(float lo, float hi) { unsigned r; asm volatile("v_cvt_pk_bf16_f32 %0, %1, %2" : "=v"(r) : "v"(lo), "v"(hi)); return r; }
; __device__ __forceinline__ float bflo(unsigned u) { return __uint_as_float(u << 16); }
; __device__ __forceinline__ float bfhi(unsigned u) { return __uint_as_float(u & 0xffff0000u); }
;     __device__ __forceinline__ void operator()(const f32x4 (&acc)[2][2][4][2], const Unit& u, int wr, int wc, int fr, int fq) const {
;     ...
;                     for (int bj = 0; bj < 2; ++bj) { bs[m][bj][0] = (f32x4){bflo(rb[m][bj].x), bfhi(rb[m][bj].x), bflo(rb[m][bj].y), bfhi(rb[m][bj].y)}; bs[m][bj][1] = (f32x4){bflo(rb[m][bj].z), bfhi(rb[m][bj].z), bflo(rb[m][bj].w), bfhi(rb[m][bj].w)}; }
;             }
; #pragma unroll
;             for (int m = 0; m < 4; ++m) { const size_t off = (size_t)(row0 + ai * HALF + m * 16) * ldc + col0; float ss = 0.f;
; #pragma unroll
;                 for (int bj = 0; bj < 2; ++bj) { const f32x4 o0 = bs[m][bj][0] + acc[ai][bj][m][0], o1 = bs[m][bj][1] + acc[ai][bj][m][1];
;                     if (outf) { *(f32x4*)(outf + off + bj * HALF) = o0; *(f32x4*)(outf + off + bj * HALF + 4) = o1; }
;                     else { ss += ((o0[0] * o0[0] + o0[1] * o0[1]) + (o0[2] * o0[2] + o0[3] * o0[3])) + ((o1[0] * o1[0] + o1[1] * o1[1]) + (o1[2] * o1[2] + o1[3] * o1[3]));
;                         u32x4 w; w.x = cvt_pk_bf16(o0[0], o0[1]); w.y = cvt_pk_bf16(o0[2], o0[3]); w.z = cvt_pk_bf16(o1[0], o1[1]); w.w = cvt_pk_bf16(o1[2], o1[3]); *(u32x4*)(outb + off + bj * HALF) = w; } }
.LBB0_235:
	v_lshlrev_b32_e32 v44, 16, v214
	v_and_b32_e32 v45, 0xffff0000, v214
	v_lshlrev_b32_e32 v46, 16, v215
	v_and_b32_e32 v47, 0xffff0000, v215
	v_lshlrev_b32_e32 v48, 16, v216
	v_and_b32_e32 v49, 0xffff0000, v216
	v_lshlrev_b32_e32 v50, 16, v217
	v_and_b32_e32 v51, 0xffff0000, v217
	v_pk_add_f32 v[42:43], v[42:43], v[46:47]
	v_pk_add_f32 v[40:41], v[40:41], v[44:45]
	v_pk_add_f32 v[38:39], v[38:39], v[50:51]
	v_pk_add_f32 v[36:37], v[36:37], v[48:49]
	s_and_b64 vcc, exec, s[42:43]
	s_mov_b64 s[18:19], -1
	s_cbranch_vccz .LBB0_238
	s_andn2_b64 vcc, exec, s[18:19]
	s_cbranch_vccz .LBB0_239

; __device__ __forceinline__ unsigned cvt_pk_bf16(float lo, float hi) { unsigned r; asm volatile("v_cvt_pk_bf16_f32 %0, %1, %2" : "=v"(r) : "v"(lo), "v"(hi)); return r; }
; __device__ __forceinline__ float bflo(unsigned u) { return __uint_as_float(u << 16); }
; __device__ __forceinline__ float bfhi(unsigned u) { return __uint_as_float(u & 0xffff0000u); }
;     __device__ __forceinline__ void operator()(const f32x4 (&acc)[2][2][4][2], const Unit& u, int wr, int wc, int fr, int fq) const {
;     ...
;                     for (int bj = 0; bj < 2; ++bj) { bs[m][bj][0] = (f32x4){bflo(rb[m][bj].x), bfhi(rb[m][bj].x), bflo(rb[m][bj].y), bfhi(rb[m][bj].y)}; bs[m][bj][1] = (f32x4){bflo(rb[m][bj].z), bfhi(rb[m][bj].z), bflo(rb[m][bj].w), bfhi(rb[m][bj].w)}; }
;             }
; #pragma unroll
;             for (int m = 0; m < 4; ++m) { const size_t off = (size_t)(row0 + ai * HALF + m * 16) * ldc + col0; float ss = 0.f;
; #pragma unroll
;                 for (int bj = 0; bj < 2; ++bj) { const f32x4 o0 = bs[m][bj][0] + acc[ai][bj][m][0], o1 = bs[m][bj][1] + acc[ai][bj][m][1];
;                     if (outf) { *(f32x4*)(outf + off + bj * HALF) = o0; *(f32x4*)(outf + off + bj * HALF + 4) = o1; }
;                     else { ss += ((o0[0] * o0[0] + o0[1] * o0[1]) + (o0[2] * o0[2] + o0[3] * o0[3])) + ((o1[0] * o1[0] + o1[1] * o1[1]) + (o1[2] * o1[2] + o1[3] * o1[3]));
;                         u32x4 w; w.x = cvt_pk_bf16(o0[0], o0[1]); w.y = cvt_pk_bf16(o0[2], o0[3]); w.z = cvt_pk_bf16(o1[0], o1[1]); w.w = cvt_pk_bf16(o1[2], o1[3]); *(u32x4*)(outb + off + bj * HALF) = w; } }
.LBB0_243:
	v_lshlrev_b32_e32 v38, 16, v218
	v_and_b32_e32 v39, 0xffff0000, v218
	v_lshlrev_b32_e32 v40, 16, v219
	v_and_b32_e32 v41, 0xffff0000, v219
	v_lshlrev_b32_e32 v42, 16, v220
	v_and_b32_e32 v43, 0xffff0000, v220
	v_lshlrev_b32_e32 v44, 16, v221
	v_and_b32_e32 v45, 0xffff0000, v221
	s_waitcnt lgkmcnt(0)
	v_lshlrev_b64 v[36:37], 10, v[98:99]
	v_lshl_add_u64 v[36:37], v[36:37], 0, v[170:171]
	v_pk_add_f32 v[34:35], v[34:35], v[40:41]
	v_pk_add_f32 v[32:33], v[32:33], v[38:39]
	v_pk_add_f32 v[30:31], v[30:31], v[44:45]
	s_cmp_eq_u64 s[18:19], 0
	v_pk_add_f32 v[28:29], v[28:29], v[42:43]
	s_cbranch_scc1 .LBB0_272
	v_lshlrev_b64 v[38:39], 2, v[36:37]
	v_lshl_add_u64 v[40:41], s[18:19], 0, v[38:39]
	v_lshl_add_u64 v[38:39], s[6:7], 0, v[38:39]
	global_store_dwordx4 v[40:41], v[32:35], off
	global_store_dwordx4 v[38:39], v[28:31], off offset:16
	v_mov_b32_e32 v40, 0
	v_lshl_add_u64 v[38:39], v[36:37], 1, s[6:7]
	s_cbranch_execnz .LBB0_246

; __device__ __forceinline__ unsigned cvt_pk_bf16(float lo, float hi) { unsigned r; asm volatile("v_cvt_pk_bf16_f32 %0, %1, %2" : "=v"(r) : "v"(lo), "v"(hi)); return r; }
; __device__ __forceinline__ float bflo(unsigned u) { return __uint_as_float(u << 16); }
; __device__ __forceinline__ float bfhi(unsigned u) { return __uint_as_float(u & 0xffff0000u); }
;     __device__ __forceinline__ void operator()(const f32x4 (&acc)[2][2][4][2], const Unit& u, int wr, int wc, int fr, int fq) const {
;     ...
;                     for (int bj = 0; bj < 2; ++bj) { bs[m][bj][0] = (f32x4){bflo(rb[m][bj].x), bfhi(rb[m][bj].x), bflo(rb[m][bj].y), bfhi(rb[m][bj].y)}; bs[m][bj][1] = (f32x4){bflo(rb[m][bj].z), bfhi(rb[m][bj].z), bflo(rb[m][bj].w), bfhi(rb[m][bj].w)}; }
;             }
; #pragma unroll
;             for (int m = 0; m < 4; ++m) { const size_t off = (size_t)(row0 + ai * HALF + m * 16) * ldc + col0; float ss = 0.f;
; #pragma unroll
;                 for (int bj = 0; bj < 2; ++bj) { const f32x4 o0 = bs[m][bj][0] + acc[ai][bj][m][0], o1 = bs[m][bj][1] + acc[ai][bj][m][1];
;                     if (outf) { *(f32x4*)(outf + off + bj * HALF) = o0; *(f32x4*)(outf + off + bj * HALF + 4) = o1; }
;                     else { ss += ((o0[0] * o0[0] + o0[1] * o0[1]) + (o0[2] * o0[2] + o0[3] * o0[3])) + ((o1[0] * o1[0] + o1[1] * o1[1]) + (o1[2] * o1[2] + o1[3] * o1[3]));
;                         u32x4 w; w.x = cvt_pk_bf16(o0[0], o0[1]); w.y = cvt_pk_bf16(o0[2], o0[3]); w.z = cvt_pk_bf16(o1[0], o1[1]); w.w = cvt_pk_bf16(o1[2], o1[3]); *(u32x4*)(outb + off + bj * HALF) = w; } }
.LBB0_246:
	v_lshlrev_b32_e32 v28, 16, v222
	v_and_b32_e32 v29, 0xffff0000, v222
	v_lshlrev_b32_e32 v30, 16, v223
	v_and_b32_e32 v31, 0xffff0000, v223
	v_lshlrev_b32_e32 v32, 16, v224
	v_and_b32_e32 v33, 0xffff0000, v224
	v_lshlrev_b32_e32 v34, 16, v225
	v_and_b32_e32 v35, 0xffff0000, v225
	v_pk_add_f32 v[26:27], v[26:27], v[30:31]
	v_pk_add_f32 v[24:25], v[24:25], v[28:29]
	v_pk_add_f32 v[22:23], v[22:23], v[34:35]
	v_pk_add_f32 v[20:21], v[20:21], v[32:33]
	s_and_b64 vcc, exec, s[42:43]
	s_mov_b64 s[18:19], -1
	s_cbranch_vccz .LBB0_249
	s_andn2_b64 vcc, exec, s[18:19]
	s_cbranch_vccz .LBB0_250

; __device__ __forceinline__ unsigned cvt_pk_bf16(float lo, float hi) { unsigned r; asm volatile("v_cvt_pk_bf16_f32 %0, %1, %2" : "=v"(r) : "v"(lo), "v"(hi)); return r; }
; __device__ __forceinline__ float bflo(unsigned u) { return __uint_as_float(u << 16); }
; __device__ __forceinline__ float bfhi(unsigned u) { return __uint_as_float(u & 0xffff0000u); }
;     __device__ __forceinline__ void operator()(const f32x4 (&acc)[2][2][4][2], const Unit& u, int wr, int wc, int fr, int fq) const {
;     ...
;                     for (int bj = 0; bj < 2; ++bj) { bs[m][bj][0] = (f32x4){bflo(rb[m][bj].x), bfhi(rb[m][bj].x), bflo(rb[m][bj].y), bfhi(rb[m][bj].y)}; bs[m][bj][1] = (f32x4){bflo(rb[m][bj].z), bfhi(rb[m][bj].z), bflo(rb[m][bj].w), bfhi(rb[m][bj].w)}; }
;             }
; #pragma unroll
;             for (int m = 0; m < 4; ++m) { const size_t off = (size_t)(row0 + ai * HALF + m * 16) * ldc + col0; float ss = 0.f;
; #pragma unroll
;                 for (int bj = 0; bj < 2; ++bj) { const f32x4 o0 = bs[m][bj][0] + acc[ai][bj][m][0], o1 = bs[m][bj][1] + acc[ai][bj][m][1];
;                     if (outf) { *(f32x4*)(outf + off + bj * HALF) = o0; *(f32x4*)(outf + off + bj * HALF + 4) = o1; }
;                     else { ss += ((o0[0] * o0[0] + o0[1] * o0[1]) + (o0[2] * o0[2] + o0[3] * o0[3])) + ((o1[0] * o1[0] + o1[1] * o1[1]) + (o1[2] * o1[2] + o1[3] * o1[3]));
;                         u32x4 w; w.x = cvt_pk_bf16(o0[0], o0[1]); w.y = cvt_pk_bf16(o0[2], o0[3]); w.z = cvt_pk_bf16(o1[0], o1[1]); w.w = cvt_pk_bf16(o1[2], o1[3]); *(u32x4*)(outb + off + bj * HALF) = w; } }
.LBB0_254:
	v_lshlrev_b32_e32 v22, 16, v226
	v_and_b32_e32 v23, 0xffff0000, v226
	v_lshlrev_b32_e32 v24, 16, v227
	v_and_b32_e32 v25, 0xffff0000, v227
	v_lshlrev_b32_e32 v26, 16, v228
	v_and_b32_e32 v27, 0xffff0000, v228
	v_lshlrev_b32_e32 v28, 16, v229
	v_and_b32_e32 v29, 0xffff0000, v229
	s_waitcnt lgkmcnt(0)
	v_lshlrev_b64 v[20:21], 10, v[96:97]
	v_lshl_add_u64 v[20:21], v[20:21], 0, v[170:171]
	v_pk_add_f32 v[18:19], v[18:19], v[24:25]
	v_pk_add_f32 v[16:17], v[16:17], v[22:23]
	v_pk_add_f32 v[14:15], v[14:15], v[28:29]
	s_cmp_eq_u64 s[18:19], 0
	v_pk_add_f32 v[12:13], v[12:13], v[26:27]
	s_cbranch_scc1 .LBB0_273
	v_lshlrev_b64 v[22:23], 2, v[20:21]
	v_lshl_add_u64 v[24:25], s[18:19], 0, v[22:23]
	v_lshl_add_u64 v[22:23], s[6:7], 0, v[22:23]
	global_store_dwordx4 v[24:25], v[16:19], off
	global_store_dwordx4 v[22:23], v[12:15], off offset:16
	v_mov_b32_e32 v24, 0
	v_lshl_add_u64 v[22:23], v[20:21], 1, s[6:7]
	s_cbranch_execnz .LBB0_257

; __device__ __forceinline__ unsigned cvt_pk_bf16(float lo, float hi) { unsigned r; asm volatile("v_cvt_pk_bf16_f32 %0, %1, %2" : "=v"(r) : "v"(lo), "v"(hi)); return r; }
; __device__ __forceinline__ float bflo(unsigned u) { return __uint_as_float(u << 16); }
; __device__ __forceinline__ float bfhi(unsigned u) { return __uint_as_float(u & 0xffff0000u); }
;     __device__ __forceinline__ void operator()(const f32x4 (&acc)[2][2][4][2], const Unit& u, int wr, int wc, int fr, int fq) const {
;     ...
;                     for (int bj = 0; bj < 2; ++bj) { bs[m][bj][0] = (f32x4){bflo(rb[m][bj].x), bfhi(rb[m][bj].x), bflo(rb[m][bj].y), bfhi(rb[m][bj].y)}; bs[m][bj][1] = (f32x4){bflo(rb[m][bj].z), bfhi(rb[m][bj].z), bflo(rb[m][bj].w), bfhi(rb[m][bj].w)}; }
;             }
; #pragma unroll
;             for (int m = 0; m < 4; ++m) { const size_t off = (size_t)(row0 + ai * HALF + m * 16) * ldc + col0; float ss = 0.f;
; #pragma unroll
;                 for (int bj = 0; bj < 2; ++bj) { const f32x4 o0 = bs[m][bj][0] + acc[ai][bj][m][0], o1 = bs[m][bj][1] + acc[ai][bj][m][1];
;                     if (outf) { *(f32x4*)(outf + off + bj * HALF) = o0; *(f32x4*)(outf + off + bj * HALF + 4) = o1; }
;                     else { ss += ((o0[0] * o0[0] + o0[1] * o0[1]) + (o0[2] * o0[2] + o0[3] * o0[3])) + ((o1[0] * o1[0] + o1[1] * o1[1]) + (o1[2] * o1[2] + o1[3] * o1[3]));
;                         u32x4 w; w.x = cvt_pk_bf16(o0[0], o0[1]); w.y = cvt_pk_bf16(o0[2], o0[3]); w.z = cvt_pk_bf16(o1[0], o1[1]); w.w = cvt_pk_bf16(o1[2], o1[3]); *(u32x4*)(outb + off + bj * HALF) = w; } }
.LBB0_257:
	v_lshlrev_b32_e32 v12, 16, v230
	v_and_b32_e32 v13, 0xffff0000, v230
	v_lshlrev_b32_e32 v14, 16, v231
	v_and_b32_e32 v15, 0xffff0000, v231
	v_lshlrev_b32_e32 v16, 16, v232
	v_and_b32_e32 v17, 0xffff0000, v232
	v_lshlrev_b32_e32 v18, 16, v233
	v_and_b32_e32 v19, 0xffff0000, v233
	v_pk_add_f32 v[10:11], v[10:11], v[14:15]
	v_pk_add_f32 v[8:9], v[8:9], v[12:13]
	v_pk_add_f32 v[6:7], v[6:7], v[18:19]
	v_pk_add_f32 v[4:5], v[4:5], v[16:17]
	s_and_b64 vcc, exec, s[42:43]
	s_mov_b64 s[18:19], -1
	s_cbranch_vccz .LBB0_260
	s_andn2_b64 vcc, exec, s[18:19]
	s_cbranch_vccz .LBB0_261
